# GEMM K-loops: the 8 redundant s_setprio 0 / s_setprio 1 pairs between back-to-back MFMA blocks deleted (role-split flips kept)
# speedup vs baseline: 1.0067x; 1.0017x over previous
; #define PG8_STAGE(bufoff, gbase, voff) do { _Pragma("unroll") for (int _i = 0; _i < 2; ++_i) \
;         __builtin_amdgcn_global_load_lds((const unsigned*)((const char*)(gbase) + (voff)[_i]), (PG8_LAS unsigned*)(lds + (bufoff) + ldsw + _i * 8192), 16, 0, 0); } while (0)
; #define PG8_LDA(dst, b, h) do { _Pragma("unroll") for (int m = 0; m < 4; ++m) _Pragma("unroll") for (int k = 0; k < 2; ++k) dst[m][k] = *(const PG8_LAS bf16x8*)(lds + PG8_SA(b, h) + aoff + m * 2048 + k * 1024); } while (0)
; #define PG8_LDB(dst, b, h) do { _Pragma("unroll") for (int n = 0; n < 2; ++n) _Pragma("unroll") for (int k = 0; k < 2; ++k) dst[n][k] = *(const PG8_LAS bf16x8*)(lds + PG8_SB(b, h) + boff + n * 2048 + k * 1024); } while (0)
; #define PG8_MMA(ai, bj, At, Bt) do { __builtin_amdgcn_s_setprio(1); _Pragma("unroll") for (int m = 0; m < 4; ++m) _Pragma("unroll") for (int n = 0; n < 2; ++n) _Pragma("unroll") for (int k = 0; k < 2; ++k) \
;         acc[ai][bj][m][n] = __builtin_amdgcn_mfma_f32_16x16x32_bf16(Bt[n][k], At[m][k], acc[ai][bj][m][n], 0, 0, 0); __builtin_amdgcn_s_setprio(0); } while (0)
; #define PG8_WAIT_V(n) asm volatile("s_waitcnt vmcnt(" #n ")" ::: "memory")
; #define PG8_WAIT_L(n) asm volatile("s_waitcnt lgkmcnt(" #n ")" ::: "memory")
; #define PG8_BAR __builtin_amdgcn_s_barrier()
; #define PG8_SCHED __builtin_amdgcn_sched_barrier(0)
; template <class Epi, class Sched, bool ALIGN_EPI = false, bool SP2 = false>
; __device__ __forceinline__ void gemm_phase(PG8_LAS unsigned char* lds, const Gemm g, const Sched& S, const Epi& E, int tid_in) {
;     ...
;             const bool last = (t == ntc - 2);
;             const char* a1 = PG8_KA(cA, t + 1);
;             const char* a2 = last ? nA : PG8_KA(cA, t + 2); const char* b2 = last ? nB : cB + (size_t)(t + 2) * kstep;
;             const char* a3 = last ? PG8_KA(nA, 1) : PG8_KA(cA, t + 3); const char* b3 = b2 + kstep;
;             if (last && has_next) S.a_ready(nxt);
;             if constexpr (SP2) {
;             PG8_LDB(B0, 0, 0); PG8_LDB(B1, 0, 1); PG8_SCHED; PG8_LDA(At, 0, 0); PG8_STAGE(PG8_SA(1, 1), a1 + hstepA, voffA);
;             PG8_WAIT_V(8); PG8_WAIT_L(0); PG8_BAR; PG8_MMA(0, 0, At, B0); PG8_MMA(0, 1, At, B1); PG8_BAR; PG8_SCHED;
;             PG8_LDA(At, 0, 1); PG8_STAGE(PG8_SB(0, 0), b2, voffB); PG8_STAGE(PG8_SB(0, 1), b2 + hstep, voffB); PG8_STAGE(PG8_SA(0, 0), a2, voffA);
.LBB0_606:
	s_or_b32 s11, s10, 1
	s_cmp_ge_u32 s11, s84
	s_cselect_b32 s27, s86, 0
	s_cselect_b32 s79, s85, 0
	s_add_i32 s23, s10, 2
	s_cmp_ge_u32 s23, s84
	s_cselect_b32 s44, s86, 0
	s_cselect_b32 s11, s85, 0
	s_add_u32 s44, s44, s0
	s_addc_u32 s11, s11, s1
	s_add_u32 s44, s2, s44
	s_addc_u32 s11, s3, s11
	s_add_u32 s44, s44, 0x100
	s_addc_u32 s11, s11, 0
	s_add_u32 s46, s20, s0
	s_addc_u32 s47, s21, s1
	s_add_i32 s10, s10, 3
	s_cmp_ge_u32 s10, s84
	s_cselect_b32 s45, s86, 0
	s_cselect_b32 s10, s85, 0
	s_add_u32 s45, s45, s0
	s_addc_u32 s10, s10, s1
	s_add_u32 s45, s2, s45
	s_addc_u32 s10, s3, s10
	s_add_u32 s78, s45, 0x180
	s_addc_u32 s10, s10, 0
	s_cmp_eq_u32 s22, s0
	s_cselect_b32 s45, s41, s11
	s_cselect_b32 s44, s40, s44
	s_cselect_b32 s47, s43, s47
	s_cselect_b32 s46, s42, s46
	s_cselect_b32 s11, s19, s10
	s_cselect_b32 s10, s18, s78
	s_add_i32 s81, 0, 0x10000
	v_add_u32_e32 v0, s81, v205
	s_add_i32 s82, 0, 0x14000
	ds_read_b128 v[134:137], v0
	ds_read_b128 v[138:141], v0 offset:1024
	ds_read_b128 v[142:145], v0 offset:2048
	ds_read_b128 v[146:149], v0 offset:3072
	v_add_u32_e32 v0, s82, v205
	ds_read_b128 v[150:153], v0
	ds_read_b128 v[154:157], v0 offset:1024
	ds_read_b128 v[158:161], v0 offset:2048
	ds_read_b128 v[162:165], v0 offset:3072
	s_add_u32 s78, s27, s0
	s_addc_u32 s79, s79, s1
	v_lshl_add_u64 v[214:215], v[130:131], 0, s[78:79]
	s_add_i32 m0, s58, 0xc000
	ds_read_b128 v[166:169], v246
	ds_read_b128 v[170:173], v246 offset:1024
	ds_read_b128 v[174:177], v246 offset:2048
	ds_read_b128 v[178:181], v246 offset:3072
	ds_read_b128 v[182:185], v246 offset:4096
	ds_read_b128 v[186:189], v246 offset:5120
	ds_read_b128 v[190:193], v246 offset:6144
	ds_read_b128 v[210:213], v246 offset:7168
	global_load_lds_dwordx4 v[214:215], off
	v_lshl_add_u64 v[214:215], v[132:133], 0, s[78:79]
	s_add_i32 m0, s58, 0xe000
	s_nop 0
	global_load_lds_dwordx4 v[214:215], off
	s_waitcnt vmcnt(8)
	s_waitcnt lgkmcnt(0)
	s_barrier
	s_setprio 1
	s_waitcnt lgkmcnt(0)
	v_mfma_f32_16x16x32_bf16 v[122:125], v[134:137], v[166:169], v[122:125]
	v_mfma_f32_16x16x32_bf16 v[114:117], v[142:145], v[166:169], v[114:117]
	v_mfma_f32_16x16x32_bf16 v[106:109], v[134:137], v[174:177], v[106:109]
	v_mfma_f32_16x16x32_bf16 v[98:101], v[142:145], v[174:177], v[98:101]
	v_mfma_f32_16x16x32_bf16 v[90:93], v[134:137], v[182:185], v[90:93]
	v_mfma_f32_16x16x32_bf16 v[82:85], v[142:145], v[182:185], v[82:85]
	v_mfma_f32_16x16x32_bf16 v[74:77], v[134:137], v[190:193], v[74:77]
	v_mfma_f32_16x16x32_bf16 v[66:69], v[142:145], v[190:193], v[66:69]
	v_mfma_f32_16x16x32_bf16 v[122:125], v[138:141], v[170:173], v[122:125]
	v_mfma_f32_16x16x32_bf16 v[114:117], v[146:149], v[170:173], v[114:117]
	v_mfma_f32_16x16x32_bf16 v[106:109], v[138:141], v[178:181], v[106:109]
	v_mfma_f32_16x16x32_bf16 v[98:101], v[146:149], v[178:181], v[98:101]
	v_mfma_f32_16x16x32_bf16 v[90:93], v[138:141], v[186:189], v[90:93]
	v_mfma_f32_16x16x32_bf16 v[82:85], v[146:149], v[186:189], v[82:85]
	v_mfma_f32_16x16x32_bf16 v[74:77], v[138:141], v[210:213], v[74:77]
	v_mfma_f32_16x16x32_bf16 v[66:69], v[146:149], v[210:213], v[66:69]
	v_mfma_f32_16x16x32_bf16 v[126:129], v[150:153], v[166:169], v[126:129]
	v_mfma_f32_16x16x32_bf16 v[118:121], v[158:161], v[166:169], v[118:121]
	v_mfma_f32_16x16x32_bf16 v[110:113], v[150:153], v[174:177], v[110:113]
	v_mfma_f32_16x16x32_bf16 v[102:105], v[158:161], v[174:177], v[102:105]
	v_mfma_f32_16x16x32_bf16 v[94:97], v[150:153], v[182:185], v[94:97]
	v_mfma_f32_16x16x32_bf16 v[86:89], v[158:161], v[182:185], v[86:89]
	v_mfma_f32_16x16x32_bf16 v[78:81], v[150:153], v[190:193], v[78:81]
	v_mfma_f32_16x16x32_bf16 v[70:73], v[158:161], v[190:193], v[70:73]
	v_mfma_f32_16x16x32_bf16 v[126:129], v[154:157], v[170:173], v[126:129]
	v_mfma_f32_16x16x32_bf16 v[118:121], v[162:165], v[170:173], v[118:121]
	v_mfma_f32_16x16x32_bf16 v[110:113], v[154:157], v[178:181], v[110:113]
	v_mfma_f32_16x16x32_bf16 v[102:105], v[162:165], v[178:181], v[102:105]
	v_mfma_f32_16x16x32_bf16 v[94:97], v[154:157], v[186:189], v[94:97]
	v_mfma_f32_16x16x32_bf16 v[86:89], v[162:165], v[186:189], v[86:89]
	v_mfma_f32_16x16x32_bf16 v[78:81], v[154:157], v[210:213], v[78:81]
	v_mfma_f32_16x16x32_bf16 v[70:73], v[162:165], v[210:213], v[70:73]
	s_setprio 0
	s_barrier
	s_add_i32 s27, s81, s55
	v_lshl_add_u64 v[214:215], s[46:47], 0, v[202:203]
	s_mov_b32 m0, s27
	ds_read_b128 v[166:169], v246 offset:16384
	ds_read_b128 v[170:173], v246 offset:17408
	ds_read_b128 v[174:177], v246 offset:18432
	ds_read_b128 v[178:181], v246 offset:19456
	ds_read_b128 v[182:185], v246 offset:20480
	ds_read_b128 v[186:189], v246 offset:21504
	ds_read_b128 v[190:193], v246 offset:22528
	ds_read_b128 v[210:213], v246 offset:23552
	global_load_lds_dwordx4 v[214:215], off
	s_add_i32 m0, s27, 0x2000
	v_lshl_add_u64 v[216:217], s[46:47], 0, v[198:199]
	s_add_u32 s46, s46, s52
	s_addc_u32 s47, s47, 0
	s_add_i32 s27, s82, s55
	global_load_lds_dwordx4 v[216:217], off
	v_lshl_add_u64 v[218:219], s[46:47], 0, v[202:203]
	s_mov_b32 m0, s27
	v_lshl_add_u64 v[220:221], s[46:47], 0, v[198:199]
	global_load_lds_dwordx4 v[218:219], off
	s_add_i32 m0, s27, 0x2000
	v_lshl_add_u64 v[234:235], s[44:45], 0, v[200:201]
	global_load_lds_dwordx4 v[220:221], off
	s_mov_b32 m0, s58
	s_nop 0
	global_load_lds_dwordx4 v[234:235], off
	v_lshl_add_u64 v[234:235], s[44:45], 0, v[196:197]
	s_mov_b32 m0, s59
	s_nop 0
	global_load_lds_dwordx4 v[234:235], off
	s_waitcnt vmcnt(8)
	s_waitcnt lgkmcnt(0)
	s_barrier
; #define PG8_STAGE(bufoff, gbase, voff) do { _Pragma("unroll") for (int _i = 0; _i < 2; ++_i) \
;         __builtin_amdgcn_global_load_lds((const unsigned*)((const char*)(gbase) + (voff)[_i]), (PG8_LAS unsigned*)(lds + (bufoff) + ldsw + _i * 8192), 16, 0, 0); } while (0)
; #define PG8_LDA(dst, b, h) do { _Pragma("unroll") for (int m = 0; m < 4; ++m) _Pragma("unroll") for (int k = 0; k < 2; ++k) dst[m][k] = *(const PG8_LAS bf16x8*)(lds + PG8_SA(b, h) + aoff + m * 2048 + k * 1024); } while (0)
; #define PG8_LDB(dst, b, h) do { _Pragma("unroll") for (int n = 0; n < 2; ++n) _Pragma("unroll") for (int k = 0; k < 2; ++k) dst[n][k] = *(const PG8_LAS bf16x8*)(lds + PG8_SB(b, h) + boff + n * 2048 + k * 1024); } while (0)
; #define PG8_MMA(ai, bj, At, Bt) do { __builtin_amdgcn_s_setprio(1); _Pragma("unroll") for (int m = 0; m < 4; ++m) _Pragma("unroll") for (int n = 0; n < 2; ++n) _Pragma("unroll") for (int k = 0; k < 2; ++k) \
;         acc[ai][bj][m][n] = __builtin_amdgcn_mfma_f32_16x16x32_bf16(Bt[n][k], At[m][k], acc[ai][bj][m][n], 0, 0, 0); __builtin_amdgcn_s_setprio(0); } while (0)
; #define PG8_WAIT_V(n) asm volatile("s_waitcnt vmcnt(" #n ")" ::: "memory")
; #define PG8_WAIT_L(n) asm volatile("s_waitcnt lgkmcnt(" #n ")" ::: "memory")
; #define PG8_BAR __builtin_amdgcn_s_barrier()
; #define PG8_SCHED __builtin_amdgcn_sched_barrier(0)
; template <class Epi, class Sched, bool ALIGN_EPI = false, bool SP2 = false>
; __device__ __forceinline__ void gemm_phase(PG8_LAS unsigned char* lds, const Gemm g, const Sched& S, const Epi& E, int tid_in) {
;     ...
;             PG8_WAIT_V(8); PG8_WAIT_L(0); PG8_BAR; PG8_MMA(1, 0, At, B0); PG8_MMA(1, 1, At, B1); PG8_BAR; PG8_SCHED;
;             PG8_LDB(B0, 1, 0); PG8_LDB(B1, 1, 1); PG8_SCHED; PG8_LDA(At, 1, 0); PG8_STAGE(PG8_SA(0, 1), a2 + hstepA, voffA);
;             PG8_WAIT_V(8); PG8_WAIT_L(0); PG8_BAR; PG8_MMA(0, 0, At, B0); PG8_MMA(0, 1, At, B1); PG8_BAR; PG8_SCHED;
	s_setprio 1
	s_waitcnt lgkmcnt(0)
	v_mfma_f32_16x16x32_bf16 v[58:61], v[134:137], v[166:169], v[58:61]
	v_mfma_f32_16x16x32_bf16 v[50:53], v[142:145], v[166:169], v[50:53]
	v_mfma_f32_16x16x32_bf16 v[42:45], v[134:137], v[174:177], v[42:45]
	v_mfma_f32_16x16x32_bf16 v[34:37], v[142:145], v[174:177], v[34:37]
	v_mfma_f32_16x16x32_bf16 v[26:29], v[134:137], v[182:185], v[26:29]
	v_mfma_f32_16x16x32_bf16 v[18:21], v[142:145], v[182:185], v[18:21]
	v_mfma_f32_16x16x32_bf16 v[10:13], v[134:137], v[190:193], v[10:13]
	v_mfma_f32_16x16x32_bf16 v[6:9], v[142:145], v[190:193], v[6:9]
	v_mfma_f32_16x16x32_bf16 v[58:61], v[138:141], v[170:173], v[58:61]
	v_mfma_f32_16x16x32_bf16 v[50:53], v[146:149], v[170:173], v[50:53]
	v_mfma_f32_16x16x32_bf16 v[42:45], v[138:141], v[178:181], v[42:45]
	v_mfma_f32_16x16x32_bf16 v[34:37], v[146:149], v[178:181], v[34:37]
	v_mfma_f32_16x16x32_bf16 v[26:29], v[138:141], v[186:189], v[26:29]
	v_mfma_f32_16x16x32_bf16 v[18:21], v[146:149], v[186:189], v[18:21]
	v_mfma_f32_16x16x32_bf16 v[10:13], v[138:141], v[210:213], v[10:13]
	v_mfma_f32_16x16x32_bf16 v[6:9], v[146:149], v[210:213], v[6:9]
	v_mfma_f32_16x16x32_bf16 v[62:65], v[150:153], v[166:169], v[62:65]
	v_mfma_f32_16x16x32_bf16 v[54:57], v[158:161], v[166:169], v[54:57]
	v_mfma_f32_16x16x32_bf16 v[46:49], v[150:153], v[174:177], v[46:49]
	v_mfma_f32_16x16x32_bf16 v[38:41], v[158:161], v[174:177], v[38:41]
	v_mfma_f32_16x16x32_bf16 v[30:33], v[150:153], v[182:185], v[30:33]
	v_mfma_f32_16x16x32_bf16 v[22:25], v[158:161], v[182:185], v[22:25]
	v_mfma_f32_16x16x32_bf16 v[14:17], v[150:153], v[190:193], v[14:17]
	v_mfma_f32_16x16x32_bf16 v[2:5], v[158:161], v[190:193], v[2:5]
	v_mfma_f32_16x16x32_bf16 v[62:65], v[154:157], v[170:173], v[62:65]
	v_mfma_f32_16x16x32_bf16 v[54:57], v[162:165], v[170:173], v[54:57]
	v_mfma_f32_16x16x32_bf16 v[46:49], v[154:157], v[178:181], v[46:49]
	v_mfma_f32_16x16x32_bf16 v[38:41], v[162:165], v[178:181], v[38:41]
	v_mfma_f32_16x16x32_bf16 v[30:33], v[154:157], v[186:189], v[30:33]
	v_mfma_f32_16x16x32_bf16 v[22:25], v[162:165], v[186:189], v[22:25]
	v_mfma_f32_16x16x32_bf16 v[14:17], v[154:157], v[210:213], v[14:17]
	v_mfma_f32_16x16x32_bf16 v[2:5], v[162:165], v[210:213], v[2:5]
	s_setprio 0
	s_barrier
	s_add_i32 s27, 0, 0x18000
	v_add_u32_e32 v0, s27, v205
	s_add_i32 s46, 0, 0x1c000
	ds_read_b128 v[134:137], v0
	ds_read_b128 v[138:141], v0 offset:1024
	ds_read_b128 v[142:145], v0 offset:2048
	ds_read_b128 v[146:149], v0 offset:3072
	v_add_u32_e32 v0, s46, v205
	ds_read_b128 v[150:153], v0
	ds_read_b128 v[154:157], v0 offset:1024
	ds_read_b128 v[158:161], v0 offset:2048
	ds_read_b128 v[162:165], v0 offset:3072
	s_add_u32 s44, s44, s28
	s_addc_u32 s45, s45, 0
	s_mov_b32 m0, s60
	v_lshl_add_u64 v[234:235], s[44:45], 0, v[200:201]
	ds_read_b128 v[166:169], v246 offset:32768
	ds_read_b128 v[170:173], v246 offset:33792
	ds_read_b128 v[174:177], v246 offset:34816
	ds_read_b128 v[178:181], v246 offset:35840
	ds_read_b128 v[182:185], v246 offset:36864
	ds_read_b128 v[186:189], v246 offset:37888
	ds_read_b128 v[190:193], v246 offset:38912
	ds_read_b128 v[210:213], v246 offset:39936
	global_load_lds_dwordx4 v[234:235], off
	v_lshl_add_u64 v[234:235], s[44:45], 0, v[196:197]
	s_mov_b32 m0, s61
	s_nop 0
	global_load_lds_dwordx4 v[234:235], off
	s_waitcnt vmcnt(8)
	s_waitcnt lgkmcnt(0)
	s_barrier
	s_setprio 1
	s_waitcnt lgkmcnt(0)
	v_mfma_f32_16x16x32_bf16 v[122:125], v[134:137], v[166:169], v[122:125]
	v_mfma_f32_16x16x32_bf16 v[114:117], v[142:145], v[166:169], v[114:117]
	v_mfma_f32_16x16x32_bf16 v[106:109], v[134:137], v[174:177], v[106:109]
	v_mfma_f32_16x16x32_bf16 v[98:101], v[142:145], v[174:177], v[98:101]
	v_mfma_f32_16x16x32_bf16 v[90:93], v[134:137], v[182:185], v[90:93]
	v_mfma_f32_16x16x32_bf16 v[82:85], v[142:145], v[182:185], v[82:85]
	v_mfma_f32_16x16x32_bf16 v[74:77], v[134:137], v[190:193], v[74:77]
	v_mfma_f32_16x16x32_bf16 v[66:69], v[142:145], v[190:193], v[66:69]
	v_mfma_f32_16x16x32_bf16 v[122:125], v[138:141], v[170:173], v[122:125]
	v_mfma_f32_16x16x32_bf16 v[114:117], v[146:149], v[170:173], v[114:117]
	v_mfma_f32_16x16x32_bf16 v[106:109], v[138:141], v[178:181], v[106:109]
	v_mfma_f32_16x16x32_bf16 v[98:101], v[146:149], v[178:181], v[98:101]
	v_mfma_f32_16x16x32_bf16 v[90:93], v[138:141], v[186:189], v[90:93]
	v_mfma_f32_16x16x32_bf16 v[82:85], v[146:149], v[186:189], v[82:85]
	v_mfma_f32_16x16x32_bf16 v[74:77], v[138:141], v[210:213], v[74:77]
	v_mfma_f32_16x16x32_bf16 v[66:69], v[146:149], v[210:213], v[66:69]
	v_mfma_f32_16x16x32_bf16 v[126:129], v[150:153], v[166:169], v[126:129]
	v_mfma_f32_16x16x32_bf16 v[118:121], v[158:161], v[166:169], v[118:121]
	v_mfma_f32_16x16x32_bf16 v[110:113], v[150:153], v[174:177], v[110:113]
	v_mfma_f32_16x16x32_bf16 v[102:105], v[158:161], v[174:177], v[102:105]
	v_mfma_f32_16x16x32_bf16 v[94:97], v[150:153], v[182:185], v[94:97]
	v_mfma_f32_16x16x32_bf16 v[86:89], v[158:161], v[182:185], v[86:89]
	v_mfma_f32_16x16x32_bf16 v[78:81], v[150:153], v[190:193], v[78:81]
	v_mfma_f32_16x16x32_bf16 v[70:73], v[158:161], v[190:193], v[70:73]
	v_mfma_f32_16x16x32_bf16 v[126:129], v[154:157], v[170:173], v[126:129]
	v_mfma_f32_16x16x32_bf16 v[118:121], v[162:165], v[170:173], v[118:121]
	v_mfma_f32_16x16x32_bf16 v[110:113], v[154:157], v[178:181], v[110:113]
	v_mfma_f32_16x16x32_bf16 v[102:105], v[162:165], v[178:181], v[102:105]
	v_mfma_f32_16x16x32_bf16 v[94:97], v[154:157], v[186:189], v[94:97]
	v_mfma_f32_16x16x32_bf16 v[86:89], v[162:165], v[186:189], v[86:89]
	v_mfma_f32_16x16x32_bf16 v[78:81], v[154:157], v[210:213], v[78:81]
	v_mfma_f32_16x16x32_bf16 v[70:73], v[162:165], v[210:213], v[70:73]
	s_setprio 0
	s_barrier
; #define PG8_STAGE(bufoff, gbase, voff) do { _Pragma("unroll") for (int _i = 0; _i < 2; ++_i) \
;         __builtin_amdgcn_global_load_lds((const unsigned*)((const char*)(gbase) + (voff)[_i]), (PG8_LAS unsigned*)(lds + (bufoff) + ldsw + _i * 8192), 16, 0, 0); } while (0)
; #define PG8_LDA(dst, b, h) do { _Pragma("unroll") for (int m = 0; m < 4; ++m) _Pragma("unroll") for (int k = 0; k < 2; ++k) dst[m][k] = *(const PG8_LAS bf16x8*)(lds + PG8_SA(b, h) + aoff + m * 2048 + k * 1024); } while (0)
; #define PG8_MMA(ai, bj, At, Bt) do { __builtin_amdgcn_s_setprio(1); _Pragma("unroll") for (int m = 0; m < 4; ++m) _Pragma("unroll") for (int n = 0; n < 2; ++n) _Pragma("unroll") for (int k = 0; k < 2; ++k) \
;         acc[ai][bj][m][n] = __builtin_amdgcn_mfma_f32_16x16x32_bf16(Bt[n][k], At[m][k], acc[ai][bj][m][n], 0, 0, 0); __builtin_amdgcn_s_setprio(0); } while (0)
; #define PG8_WAIT_V(n) asm volatile("s_waitcnt vmcnt(" #n ")" ::: "memory")
; #define PG8_WAIT_L(n) asm volatile("s_waitcnt lgkmcnt(" #n ")" ::: "memory")
; #define PG8_BAR __builtin_amdgcn_s_barrier()
; #define PG8_SCHED __builtin_amdgcn_sched_barrier(0)
; template <class Epi, class Sched, bool ALIGN_EPI = false, bool SP2 = false>
; __device__ __forceinline__ void gemm_phase(PG8_LAS unsigned char* lds, const Gemm g, const Sched& S, const Epi& E, int tid_in) {
;     ...
;             PG8_LDA(At, 1, 1); PG8_STAGE(PG8_SB(1, 0), b3, voffB); PG8_STAGE(PG8_SB(1, 1), b3 + hstep, voffB); PG8_STAGE(PG8_SA(1, 0), a3, voffA);
;             PG8_WAIT_V(8); PG8_WAIT_L(0); PG8_BAR; PG8_MMA(1, 0, At, B0); PG8_MMA(1, 1, At, B1); PG8_BAR; PG8_SCHED;
	s_add_i32 s27, s27, s55
	v_lshl_add_u64 v[214:215], v[214:215], 0, s[96:97]
	s_mov_b32 m0, s27
	ds_read_b128 v[166:169], v246 offset:49152
	ds_read_b128 v[170:173], v246 offset:50176
	ds_read_b128 v[174:177], v246 offset:51200
	ds_read_b128 v[178:181], v246 offset:52224
	ds_read_b128 v[182:185], v246 offset:53248
	ds_read_b128 v[186:189], v246 offset:54272
	ds_read_b128 v[190:193], v246 offset:55296
	ds_read_b128 v[210:213], v246 offset:56320
	global_load_lds_dwordx4 v[214:215], off
	v_lshl_add_u64 v[214:215], v[216:217], 0, s[96:97]
	s_add_i32 m0, s27, 0x2000
	s_add_i32 s27, s46, s55
	global_load_lds_dwordx4 v[214:215], off
	v_lshl_add_u64 v[214:215], v[218:219], 0, s[96:97]
	s_mov_b32 m0, s27
	s_nop 0
	global_load_lds_dwordx4 v[214:215], off
	v_lshl_add_u64 v[214:215], v[220:221], 0, s[96:97]
	s_add_i32 m0, s27, 0x2000
	s_nop 0
	global_load_lds_dwordx4 v[214:215], off
	v_lshl_add_u64 v[214:215], s[10:11], 0, v[200:201]
	s_mov_b32 m0, s63
	s_nop 0
	global_load_lds_dwordx4 v[214:215], off
	v_lshl_add_u64 v[214:215], s[10:11], 0, v[196:197]
	s_mov_b32 m0, s64
	s_nop 0
	global_load_lds_dwordx4 v[214:215], off
	s_waitcnt vmcnt(8)
	s_waitcnt lgkmcnt(0)
	s_barrier
	s_setprio 1
	s_waitcnt lgkmcnt(0)
	v_mfma_f32_16x16x32_bf16 v[58:61], v[134:137], v[166:169], v[58:61]
	v_mfma_f32_16x16x32_bf16 v[50:53], v[142:145], v[166:169], v[50:53]
	v_mfma_f32_16x16x32_bf16 v[42:45], v[134:137], v[174:177], v[42:45]
	v_mfma_f32_16x16x32_bf16 v[34:37], v[142:145], v[174:177], v[34:37]
	v_mfma_f32_16x16x32_bf16 v[26:29], v[134:137], v[182:185], v[26:29]
	v_mfma_f32_16x16x32_bf16 v[18:21], v[142:145], v[182:185], v[18:21]
	v_mfma_f32_16x16x32_bf16 v[10:13], v[134:137], v[190:193], v[10:13]
	v_mfma_f32_16x16x32_bf16 v[6:9], v[142:145], v[190:193], v[6:9]
	v_mfma_f32_16x16x32_bf16 v[58:61], v[138:141], v[170:173], v[58:61]
	v_mfma_f32_16x16x32_bf16 v[50:53], v[146:149], v[170:173], v[50:53]
	v_mfma_f32_16x16x32_bf16 v[42:45], v[138:141], v[178:181], v[42:45]
	v_mfma_f32_16x16x32_bf16 v[34:37], v[146:149], v[178:181], v[34:37]
	v_mfma_f32_16x16x32_bf16 v[26:29], v[138:141], v[186:189], v[26:29]
	v_mfma_f32_16x16x32_bf16 v[18:21], v[146:149], v[186:189], v[18:21]
	v_mfma_f32_16x16x32_bf16 v[10:13], v[138:141], v[210:213], v[10:13]
	v_mfma_f32_16x16x32_bf16 v[6:9], v[146:149], v[210:213], v[6:9]
	v_mfma_f32_16x16x32_bf16 v[62:65], v[150:153], v[166:169], v[62:65]
	v_mfma_f32_16x16x32_bf16 v[54:57], v[158:161], v[166:169], v[54:57]
	v_mfma_f32_16x16x32_bf16 v[46:49], v[150:153], v[174:177], v[46:49]
	v_mfma_f32_16x16x32_bf16 v[38:41], v[158:161], v[174:177], v[38:41]
	v_mfma_f32_16x16x32_bf16 v[30:33], v[150:153], v[182:185], v[30:33]
	v_mfma_f32_16x16x32_bf16 v[22:25], v[158:161], v[182:185], v[22:25]
	v_mfma_f32_16x16x32_bf16 v[14:17], v[150:153], v[190:193], v[14:17]
	v_mfma_f32_16x16x32_bf16 v[2:5], v[158:161], v[190:193], v[2:5]
	v_mfma_f32_16x16x32_bf16 v[62:65], v[154:157], v[170:173], v[62:65]
	v_mfma_f32_16x16x32_bf16 v[54:57], v[162:165], v[170:173], v[54:57]
	v_mfma_f32_16x16x32_bf16 v[46:49], v[154:157], v[178:181], v[46:49]
	v_mfma_f32_16x16x32_bf16 v[38:41], v[162:165], v[178:181], v[38:41]
	v_mfma_f32_16x16x32_bf16 v[30:33], v[154:157], v[186:189], v[30:33]
	v_mfma_f32_16x16x32_bf16 v[22:25], v[162:165], v[186:189], v[22:25]
	v_mfma_f32_16x16x32_bf16 v[14:17], v[154:157], v[210:213], v[14:17]
	v_mfma_f32_16x16x32_bf16 v[2:5], v[162:165], v[210:213], v[2:5]
	s_setprio 0
	s_barrier
	s_add_u32 s0, s0, 0x100
	s_addc_u32 s1, s1, 0
	s_cmp_ge_u32 s23, s94
	s_mov_b32 s10, s23
	s_cbranch_scc0 .LBB0_606
	v_readlane_b32 s90, v254, 43
	v_readlane_b32 s91, v254, 44
	s_and_b64 vcc, exec, s[34:35]
	s_cbranch_vccz .LBB0_609

; #define PG8_STAGE(bufoff, gbase, voff) do { _Pragma("unroll") for (int _i = 0; _i < 2; ++_i) \
;         __builtin_amdgcn_global_load_lds((const unsigned*)((const char*)(gbase) + (voff)[_i]), (PG8_LAS unsigned*)(lds + (bufoff) + ldsw + _i * 8192), 16, 0, 0); } while (0)
; #define PG8_LDA(dst, b, h) do { _Pragma("unroll") for (int m = 0; m < 4; ++m) _Pragma("unroll") for (int k = 0; k < 2; ++k) dst[m][k] = *(const PG8_LAS bf16x8*)(lds + PG8_SA(b, h) + aoff + m * 2048 + k * 1024); } while (0)
; #define PG8_LDB(dst, b, h) do { _Pragma("unroll") for (int n = 0; n < 2; ++n) _Pragma("unroll") for (int k = 0; k < 2; ++k) dst[n][k] = *(const PG8_LAS bf16x8*)(lds + PG8_SB(b, h) + boff + n * 2048 + k * 1024); } while (0)
; #define PG8_MMA(ai, bj, At, Bt) do { __builtin_amdgcn_s_setprio(1); _Pragma("unroll") for (int m = 0; m < 4; ++m) _Pragma("unroll") for (int n = 0; n < 2; ++n) _Pragma("unroll") for (int k = 0; k < 2; ++k) \
;         acc[ai][bj][m][n] = __builtin_amdgcn_mfma_f32_16x16x32_bf16(Bt[n][k], At[m][k], acc[ai][bj][m][n], 0, 0, 0); __builtin_amdgcn_s_setprio(0); } while (0)
; #define PG8_WAIT_V(n) asm volatile("s_waitcnt vmcnt(" #n ")" ::: "memory")
; #define PG8_WAIT_L(n) asm volatile("s_waitcnt lgkmcnt(" #n ")" ::: "memory")
; #define PG8_BAR __builtin_amdgcn_s_barrier()
; #define PG8_SCHED __builtin_amdgcn_sched_barrier(0)
; template <class Epi, class Sched, bool ALIGN_EPI = false, bool SP2 = false>
; __device__ __forceinline__ void gemm_phase(PG8_LAS unsigned char* lds, const Gemm g, const Sched& S, const Epi& E, int tid_in) {
;     ...
;             const bool last = (t == ntc - 2);
;             const char* a1 = PG8_KA(cA, t + 1);
;             const char* a2 = last ? nA : PG8_KA(cA, t + 2); const char* b2 = last ? nB : cB + (size_t)(t + 2) * kstep;
;             const char* a3 = last ? PG8_KA(nA, 1) : PG8_KA(cA, t + 3); const char* b3 = b2 + kstep;
;             if (last && has_next) S.a_ready(nxt);
;             if constexpr (SP2) {
;             PG8_LDB(B0, 0, 0); PG8_LDB(B1, 0, 1); PG8_SCHED; PG8_LDA(At, 0, 0); PG8_STAGE(PG8_SA(1, 1), a1 + hstepA, voffA);
;             PG8_WAIT_V(8); PG8_WAIT_L(0); PG8_BAR; PG8_MMA(0, 0, At, B0); PG8_MMA(0, 1, At, B1); PG8_BAR; PG8_SCHED;
;             PG8_LDA(At, 0, 1); PG8_STAGE(PG8_SB(0, 0), b2, voffB); PG8_STAGE(PG8_SB(0, 1), b2 + hstep, voffB); PG8_STAGE(PG8_SA(0, 0), a2, voffA);
.LBB0_1180:
	s_or_b32 s1, s0, 1
	s_cmp_ge_u32 s1, s84
	s_cselect_b32 s58, s86, 0
	s_cselect_b32 s59, s85, 0
	s_add_i32 s57, s0, 2
	s_cmp_ge_u32 s57, s84
	s_cselect_b32 s8, s86, 0
	s_cselect_b32 s1, s85, 0
	s_add_u32 s8, s6, s8
	s_addc_u32 s1, s7, s1
	s_add_u32 s8, s8, 0x100
	s_addc_u32 s1, s1, 0
	s_add_i32 s0, s0, 3
	s_cmp_ge_u32 s0, s84
	s_cselect_b32 s9, s86, 0
	s_cselect_b32 s0, s85, 0
	s_add_u32 s9, s6, s9
	s_addc_u32 s0, s7, s0
	s_add_u32 s62, s9, 0x180
	s_addc_u32 s0, s0, 0
	s_cmp_eq_u32 s56, 0
	s_cselect_b32 s9, s49, s1
	s_cselect_b32 s8, s48, s8
	s_cselect_b32 s61, s51, s55
	s_cselect_b32 s60, s50, s54
	s_cselect_b32 s1, s53, s0
	s_cselect_b32 s0, s21, s62
	s_add_i32 s62, 0, 0x10000
	v_add_u32_e32 v0, s62, v207
	s_add_i32 s63, 0, 0x14000
	ds_read_b128 v[132:135], v0
	ds_read_b128 v[136:139], v0 offset:1024
	ds_read_b128 v[140:143], v0 offset:2048
	ds_read_b128 v[144:147], v0 offset:3072
	v_add_u32_e32 v0, s63, v207
	ds_read_b128 v[148:151], v0
	ds_read_b128 v[152:155], v0 offset:1024
	ds_read_b128 v[156:159], v0 offset:2048
	ds_read_b128 v[160:163], v0 offset:3072
	v_lshl_add_u64 v[2:3], s[6:7], 0, v[180:181]
	v_lshl_add_u64 v[2:3], v[2:3], 0, s[58:59]
	s_add_i32 m0, s89, 0xc000
	ds_read_b128 v[164:167], v208
	ds_read_b128 v[168:171], v208 offset:1024
	ds_read_b128 v[184:187], v208 offset:2048
	ds_read_b128 v[188:191], v208 offset:3072
	ds_read_b128 v[196:199], v208 offset:4096
	ds_read_b128 v[200:203], v208 offset:5120
	ds_read_b128 v[210:213], v208 offset:6144
	ds_read_b128 v[214:217], v208 offset:7168
	global_load_lds_dwordx4 v[2:3], off
	v_lshl_add_u64 v[2:3], s[6:7], 0, v[182:183]
	v_lshl_add_u64 v[2:3], v[2:3], 0, s[58:59]
	s_add_i32 m0, s89, 0xe000
	s_nop 0
	global_load_lds_dwordx4 v[2:3], off
	s_waitcnt vmcnt(8)
	s_waitcnt lgkmcnt(0)
	s_barrier
	s_setprio 1
	s_waitcnt lgkmcnt(0)
	v_mfma_f32_16x16x32_bf16 v[124:127], v[132:135], v[164:167], v[124:127]
	v_mfma_f32_16x16x32_bf16 v[116:119], v[140:143], v[164:167], v[116:119]
	v_mfma_f32_16x16x32_bf16 v[108:111], v[132:135], v[184:187], v[108:111]
	v_mfma_f32_16x16x32_bf16 v[100:103], v[140:143], v[184:187], v[100:103]
	v_mfma_f32_16x16x32_bf16 v[92:95], v[132:135], v[196:199], v[92:95]
	v_mfma_f32_16x16x32_bf16 v[84:87], v[140:143], v[196:199], v[84:87]
	v_mfma_f32_16x16x32_bf16 v[76:79], v[132:135], v[210:213], v[76:79]
	v_mfma_f32_16x16x32_bf16 v[68:71], v[140:143], v[210:213], v[68:71]
	v_mfma_f32_16x16x32_bf16 v[124:127], v[136:139], v[168:171], v[124:127]
	v_mfma_f32_16x16x32_bf16 v[116:119], v[144:147], v[168:171], v[116:119]
	v_mfma_f32_16x16x32_bf16 v[108:111], v[136:139], v[188:191], v[108:111]
	v_mfma_f32_16x16x32_bf16 v[100:103], v[144:147], v[188:191], v[100:103]
	v_mfma_f32_16x16x32_bf16 v[92:95], v[136:139], v[200:203], v[92:95]
	v_mfma_f32_16x16x32_bf16 v[84:87], v[144:147], v[200:203], v[84:87]
	v_mfma_f32_16x16x32_bf16 v[76:79], v[136:139], v[214:217], v[76:79]
	v_mfma_f32_16x16x32_bf16 v[68:71], v[144:147], v[214:217], v[68:71]
	v_mfma_f32_16x16x32_bf16 v[128:131], v[148:151], v[164:167], v[128:131]
	v_mfma_f32_16x16x32_bf16 v[120:123], v[156:159], v[164:167], v[120:123]
	v_mfma_f32_16x16x32_bf16 v[112:115], v[148:151], v[184:187], v[112:115]
	v_mfma_f32_16x16x32_bf16 v[104:107], v[156:159], v[184:187], v[104:107]
	v_mfma_f32_16x16x32_bf16 v[96:99], v[148:151], v[196:199], v[96:99]
	v_mfma_f32_16x16x32_bf16 v[88:91], v[156:159], v[196:199], v[88:91]
	v_mfma_f32_16x16x32_bf16 v[80:83], v[148:151], v[210:213], v[80:83]
	v_mfma_f32_16x16x32_bf16 v[72:75], v[156:159], v[210:213], v[72:75]
	v_mfma_f32_16x16x32_bf16 v[128:131], v[152:155], v[168:171], v[128:131]
	v_mfma_f32_16x16x32_bf16 v[120:123], v[160:163], v[168:171], v[120:123]
	v_mfma_f32_16x16x32_bf16 v[112:115], v[152:155], v[188:191], v[112:115]
	v_mfma_f32_16x16x32_bf16 v[104:107], v[160:163], v[188:191], v[104:107]
	v_mfma_f32_16x16x32_bf16 v[96:99], v[152:155], v[200:203], v[96:99]
	v_mfma_f32_16x16x32_bf16 v[88:91], v[160:163], v[200:203], v[88:91]
	v_mfma_f32_16x16x32_bf16 v[80:83], v[152:155], v[214:217], v[80:83]
	v_mfma_f32_16x16x32_bf16 v[72:75], v[160:163], v[214:217], v[72:75]
	s_setprio 0
	s_barrier
	s_add_i32 s58, s62, s88
	v_lshl_add_u64 v[192:193], s[60:61], 0, v[178:179]
	s_mov_b32 m0, s58
	ds_read_b128 v[164:167], v208 offset:16384
	ds_read_b128 v[168:171], v208 offset:17408
	ds_read_b128 v[184:187], v208 offset:18432
	ds_read_b128 v[188:191], v208 offset:19456
	ds_read_b128 v[196:199], v208 offset:20480
	ds_read_b128 v[200:203], v208 offset:21504
	ds_read_b128 v[210:213], v208 offset:22528
	ds_read_b128 v[214:217], v208 offset:23552
	global_load_lds_dwordx4 v[192:193], off
	s_add_i32 m0, s58, 0x2000
	s_add_u32 s58, s60, s94
	v_lshl_add_u64 v[204:205], s[60:61], 0, v[174:175]
	s_addc_u32 s59, s61, 0
	s_add_i32 s60, s63, s88
	global_load_lds_dwordx4 v[204:205], off
	v_lshl_add_u64 v[218:219], s[58:59], 0, v[178:179]
	s_mov_b32 m0, s60
	v_lshl_add_u64 v[220:221], s[58:59], 0, v[174:175]
	global_load_lds_dwordx4 v[218:219], off
	s_add_i32 m0, s60, 0x2000
	v_lshl_add_u64 v[2:3], s[8:9], 0, v[176:177]
	global_load_lds_dwordx4 v[220:221], off
	s_mov_b32 m0, s89
	s_nop 0
	global_load_lds_dwordx4 v[2:3], off
	v_lshl_add_u64 v[2:3], s[8:9], 0, v[172:173]
	s_mov_b32 m0, s90
	s_nop 0
	global_load_lds_dwordx4 v[2:3], off
	s_waitcnt vmcnt(8)
	s_waitcnt lgkmcnt(0)
	s_barrier
; #define PG8_STAGE(bufoff, gbase, voff) do { _Pragma("unroll") for (int _i = 0; _i < 2; ++_i) \
;         __builtin_amdgcn_global_load_lds((const unsigned*)((const char*)(gbase) + (voff)[_i]), (PG8_LAS unsigned*)(lds + (bufoff) + ldsw + _i * 8192), 16, 0, 0); } while (0)
; #define PG8_LDA(dst, b, h) do { _Pragma("unroll") for (int m = 0; m < 4; ++m) _Pragma("unroll") for (int k = 0; k < 2; ++k) dst[m][k] = *(const PG8_LAS bf16x8*)(lds + PG8_SA(b, h) + aoff + m * 2048 + k * 1024); } while (0)
; #define PG8_LDB(dst, b, h) do { _Pragma("unroll") for (int n = 0; n < 2; ++n) _Pragma("unroll") for (int k = 0; k < 2; ++k) dst[n][k] = *(const PG8_LAS bf16x8*)(lds + PG8_SB(b, h) + boff + n * 2048 + k * 1024); } while (0)
; #define PG8_MMA(ai, bj, At, Bt) do { __builtin_amdgcn_s_setprio(1); _Pragma("unroll") for (int m = 0; m < 4; ++m) _Pragma("unroll") for (int n = 0; n < 2; ++n) _Pragma("unroll") for (int k = 0; k < 2; ++k) \
;         acc[ai][bj][m][n] = __builtin_amdgcn_mfma_f32_16x16x32_bf16(Bt[n][k], At[m][k], acc[ai][bj][m][n], 0, 0, 0); __builtin_amdgcn_s_setprio(0); } while (0)
; #define PG8_WAIT_V(n) asm volatile("s_waitcnt vmcnt(" #n ")" ::: "memory")
; #define PG8_WAIT_L(n) asm volatile("s_waitcnt lgkmcnt(" #n ")" ::: "memory")
; #define PG8_BAR __builtin_amdgcn_s_barrier()
; #define PG8_SCHED __builtin_amdgcn_sched_barrier(0)
; template <class Epi, class Sched, bool ALIGN_EPI = false, bool SP2 = false>
; __device__ __forceinline__ void gemm_phase(PG8_LAS unsigned char* lds, const Gemm g, const Sched& S, const Epi& E, int tid_in) {
;     ...
;             PG8_WAIT_V(8); PG8_WAIT_L(0); PG8_BAR; PG8_MMA(1, 0, At, B0); PG8_MMA(1, 1, At, B1); PG8_BAR; PG8_SCHED;
;             PG8_LDB(B0, 1, 0); PG8_LDB(B1, 1, 1); PG8_SCHED; PG8_LDA(At, 1, 0); PG8_STAGE(PG8_SA(0, 1), a2 + hstepA, voffA);
;             PG8_WAIT_V(8); PG8_WAIT_L(0); PG8_BAR; PG8_MMA(0, 0, At, B0); PG8_MMA(0, 1, At, B1); PG8_BAR; PG8_SCHED;
	s_setprio 1
	s_waitcnt lgkmcnt(0)
	v_mfma_f32_16x16x32_bf16 v[60:63], v[132:135], v[164:167], v[60:63]
	v_mfma_f32_16x16x32_bf16 v[52:55], v[140:143], v[164:167], v[52:55]
	v_mfma_f32_16x16x32_bf16 v[44:47], v[132:135], v[184:187], v[44:47]
	v_mfma_f32_16x16x32_bf16 v[36:39], v[140:143], v[184:187], v[36:39]
	v_mfma_f32_16x16x32_bf16 v[28:31], v[132:135], v[196:199], v[28:31]
	v_mfma_f32_16x16x32_bf16 v[20:23], v[140:143], v[196:199], v[20:23]
	v_mfma_f32_16x16x32_bf16 v[12:15], v[132:135], v[210:213], v[12:15]
	v_mfma_f32_16x16x32_bf16 v[2:5], v[140:143], v[210:213], v[4:7]
	v_mfma_f32_16x16x32_bf16 v[60:63], v[136:139], v[168:171], v[60:63]
	v_mfma_f32_16x16x32_bf16 v[52:55], v[144:147], v[168:171], v[52:55]
	v_mfma_f32_16x16x32_bf16 v[44:47], v[136:139], v[188:191], v[44:47]
	v_mfma_f32_16x16x32_bf16 v[36:39], v[144:147], v[188:191], v[36:39]
	v_mfma_f32_16x16x32_bf16 v[28:31], v[136:139], v[200:203], v[28:31]
	v_mfma_f32_16x16x32_bf16 v[20:23], v[144:147], v[200:203], v[20:23]
	v_mfma_f32_16x16x32_bf16 v[12:15], v[136:139], v[214:217], v[12:15]
	v_mfma_f32_16x16x32_bf16 v[2:5], v[144:147], v[214:217], v[2:5]
	v_mfma_f32_16x16x32_bf16 v[64:67], v[148:151], v[164:167], v[64:67]
	v_mfma_f32_16x16x32_bf16 v[56:59], v[156:159], v[164:167], v[56:59]
	v_mfma_f32_16x16x32_bf16 v[48:51], v[148:151], v[184:187], v[48:51]
	v_mfma_f32_16x16x32_bf16 v[40:43], v[156:159], v[184:187], v[40:43]
	v_mfma_f32_16x16x32_bf16 v[32:35], v[148:151], v[196:199], v[32:35]
	v_mfma_f32_16x16x32_bf16 v[24:27], v[156:159], v[196:199], v[24:27]
	v_mfma_f32_16x16x32_bf16 v[16:19], v[148:151], v[210:213], v[16:19]
	v_mfma_f32_16x16x32_bf16 v[6:9], v[156:159], v[210:213], v[8:11]
	v_mfma_f32_16x16x32_bf16 v[64:67], v[152:155], v[168:171], v[64:67]
	v_mfma_f32_16x16x32_bf16 v[56:59], v[160:163], v[168:171], v[56:59]
	v_mfma_f32_16x16x32_bf16 v[48:51], v[152:155], v[188:191], v[48:51]
	v_mfma_f32_16x16x32_bf16 v[40:43], v[160:163], v[188:191], v[40:43]
	v_mfma_f32_16x16x32_bf16 v[32:35], v[152:155], v[200:203], v[32:35]
	v_mfma_f32_16x16x32_bf16 v[24:27], v[160:163], v[200:203], v[24:27]
	v_mfma_f32_16x16x32_bf16 v[16:19], v[152:155], v[214:217], v[16:19]
	v_mfma_f32_16x16x32_bf16 v[8:11], v[160:163], v[214:217], v[6:9]
	s_setprio 0
	s_barrier
	s_add_i32 s58, 0, 0x18000
	v_add_u32_e32 v0, s58, v207
	s_add_i32 s59, 0, 0x1c000
	ds_read_b128 v[132:135], v0
	ds_read_b128 v[136:139], v0 offset:1024
	ds_read_b128 v[140:143], v0 offset:2048
	ds_read_b128 v[144:147], v0 offset:3072
	v_add_u32_e32 v0, s59, v207
	ds_read_b128 v[148:151], v0
	ds_read_b128 v[152:155], v0 offset:1024
	ds_read_b128 v[156:159], v0 offset:2048
	ds_read_b128 v[160:163], v0 offset:3072
	s_add_u32 s8, s8, s94
	s_addc_u32 s9, s9, 0
	s_mov_b32 m0, s91
	v_lshl_add_u64 v[6:7], s[8:9], 0, v[176:177]
	ds_read_b128 v[164:167], v208 offset:32768
	ds_read_b128 v[168:171], v208 offset:33792
	ds_read_b128 v[184:187], v208 offset:34816
	ds_read_b128 v[188:191], v208 offset:35840
	ds_read_b128 v[196:199], v208 offset:36864
	ds_read_b128 v[200:203], v208 offset:37888
	ds_read_b128 v[210:213], v208 offset:38912
	ds_read_b128 v[214:217], v208 offset:39936
	global_load_lds_dwordx4 v[6:7], off
	v_lshl_add_u64 v[6:7], s[8:9], 0, v[172:173]
	s_mov_b32 m0, s92
	s_nop 0
	global_load_lds_dwordx4 v[6:7], off
	s_waitcnt vmcnt(8)
	s_waitcnt lgkmcnt(0)
	s_barrier
	s_setprio 1
	s_waitcnt lgkmcnt(0)
	v_mfma_f32_16x16x32_bf16 v[124:127], v[132:135], v[164:167], v[124:127]
	v_mfma_f32_16x16x32_bf16 v[116:119], v[140:143], v[164:167], v[116:119]
	v_mfma_f32_16x16x32_bf16 v[108:111], v[132:135], v[184:187], v[108:111]
	v_mfma_f32_16x16x32_bf16 v[100:103], v[140:143], v[184:187], v[100:103]
	v_mfma_f32_16x16x32_bf16 v[92:95], v[132:135], v[196:199], v[92:95]
	v_mfma_f32_16x16x32_bf16 v[84:87], v[140:143], v[196:199], v[84:87]
	v_mfma_f32_16x16x32_bf16 v[76:79], v[132:135], v[210:213], v[76:79]
	v_mfma_f32_16x16x32_bf16 v[68:71], v[140:143], v[210:213], v[68:71]
	v_mfma_f32_16x16x32_bf16 v[124:127], v[136:139], v[168:171], v[124:127]
	v_mfma_f32_16x16x32_bf16 v[116:119], v[144:147], v[168:171], v[116:119]
	v_mfma_f32_16x16x32_bf16 v[108:111], v[136:139], v[188:191], v[108:111]
	v_mfma_f32_16x16x32_bf16 v[100:103], v[144:147], v[188:191], v[100:103]
	v_mfma_f32_16x16x32_bf16 v[92:95], v[136:139], v[200:203], v[92:95]
	v_mfma_f32_16x16x32_bf16 v[84:87], v[144:147], v[200:203], v[84:87]
	v_mfma_f32_16x16x32_bf16 v[76:79], v[136:139], v[214:217], v[76:79]
	v_mfma_f32_16x16x32_bf16 v[68:71], v[144:147], v[214:217], v[68:71]
	v_mfma_f32_16x16x32_bf16 v[128:131], v[148:151], v[164:167], v[128:131]
	v_mfma_f32_16x16x32_bf16 v[120:123], v[156:159], v[164:167], v[120:123]
	v_mfma_f32_16x16x32_bf16 v[112:115], v[148:151], v[184:187], v[112:115]
	v_mfma_f32_16x16x32_bf16 v[104:107], v[156:159], v[184:187], v[104:107]
	v_mfma_f32_16x16x32_bf16 v[96:99], v[148:151], v[196:199], v[96:99]
	v_mfma_f32_16x16x32_bf16 v[88:91], v[156:159], v[196:199], v[88:91]
	v_mfma_f32_16x16x32_bf16 v[80:83], v[148:151], v[210:213], v[80:83]
	v_mfma_f32_16x16x32_bf16 v[72:75], v[156:159], v[210:213], v[72:75]
	v_mfma_f32_16x16x32_bf16 v[128:131], v[152:155], v[168:171], v[128:131]
	v_mfma_f32_16x16x32_bf16 v[120:123], v[160:163], v[168:171], v[120:123]
	v_mfma_f32_16x16x32_bf16 v[112:115], v[152:155], v[188:191], v[112:115]
	v_mfma_f32_16x16x32_bf16 v[104:107], v[160:163], v[188:191], v[104:107]
	v_mfma_f32_16x16x32_bf16 v[96:99], v[152:155], v[200:203], v[96:99]
	v_mfma_f32_16x16x32_bf16 v[88:91], v[160:163], v[200:203], v[88:91]
	v_mfma_f32_16x16x32_bf16 v[80:83], v[152:155], v[214:217], v[80:83]
	v_mfma_f32_16x16x32_bf16 v[72:75], v[160:163], v[214:217], v[72:75]
	s_setprio 0
	s_barrier
; #define PG8_STAGE(bufoff, gbase, voff) do { _Pragma("unroll") for (int _i = 0; _i < 2; ++_i) \
;         __builtin_amdgcn_global_load_lds((const unsigned*)((const char*)(gbase) + (voff)[_i]), (PG8_LAS unsigned*)(lds + (bufoff) + ldsw + _i * 8192), 16, 0, 0); } while (0)
; #define PG8_LDA(dst, b, h) do { _Pragma("unroll") for (int m = 0; m < 4; ++m) _Pragma("unroll") for (int k = 0; k < 2; ++k) dst[m][k] = *(const PG8_LAS bf16x8*)(lds + PG8_SA(b, h) + aoff + m * 2048 + k * 1024); } while (0)
; #define PG8_MMA(ai, bj, At, Bt) do { __builtin_amdgcn_s_setprio(1); _Pragma("unroll") for (int m = 0; m < 4; ++m) _Pragma("unroll") for (int n = 0; n < 2; ++n) _Pragma("unroll") for (int k = 0; k < 2; ++k) \
;         acc[ai][bj][m][n] = __builtin_amdgcn_mfma_f32_16x16x32_bf16(Bt[n][k], At[m][k], acc[ai][bj][m][n], 0, 0, 0); __builtin_amdgcn_s_setprio(0); } while (0)
; #define PG8_WAIT_V(n) asm volatile("s_waitcnt vmcnt(" #n ")" ::: "memory")
; #define PG8_WAIT_L(n) asm volatile("s_waitcnt lgkmcnt(" #n ")" ::: "memory")
; #define PG8_BAR __builtin_amdgcn_s_barrier()
; #define PG8_SCHED __builtin_amdgcn_sched_barrier(0)
; template <class Epi, class Sched, bool ALIGN_EPI = false, bool SP2 = false>
; __device__ __forceinline__ void gemm_phase(PG8_LAS unsigned char* lds, const Gemm g, const Sched& S, const Epi& E, int tid_in) {
;     ...
;             PG8_LDA(At, 1, 1); PG8_STAGE(PG8_SB(1, 0), b3, voffB); PG8_STAGE(PG8_SB(1, 1), b3 + hstep, voffB); PG8_STAGE(PG8_SA(1, 0), a3, voffA);
;             PG8_WAIT_V(8); PG8_WAIT_L(0); PG8_BAR; PG8_MMA(1, 0, At, B0); PG8_MMA(1, 1, At, B1); PG8_BAR; PG8_SCHED;
;     ...
;         if constexpr (ALIGN_EPI) { if (wr == 0) PG8_BAR; }
	s_add_i32 s8, s58, s88
	v_lshl_add_u64 v[6:7], v[192:193], 0, s[96:97]
	s_mov_b32 m0, s8
	ds_read_b128 v[164:167], v208 offset:49152
	ds_read_b128 v[168:171], v208 offset:50176
	ds_read_b128 v[184:187], v208 offset:51200
	ds_read_b128 v[188:191], v208 offset:52224
	ds_read_b128 v[196:199], v208 offset:53248
	ds_read_b128 v[200:203], v208 offset:54272
	ds_read_b128 v[210:213], v208 offset:55296
	ds_read_b128 v[214:217], v208 offset:56320
	global_load_lds_dwordx4 v[6:7], off
	v_lshl_add_u64 v[6:7], v[204:205], 0, s[96:97]
	s_add_i32 m0, s8, 0x2000
	s_add_i32 s8, s59, s88
	global_load_lds_dwordx4 v[6:7], off
	v_lshl_add_u64 v[6:7], v[218:219], 0, s[96:97]
	s_mov_b32 m0, s8
	s_nop 0
	global_load_lds_dwordx4 v[6:7], off
	v_lshl_add_u64 v[6:7], v[220:221], 0, s[96:97]
	s_add_i32 m0, s8, 0x2000
	s_nop 0
	global_load_lds_dwordx4 v[6:7], off
	v_lshl_add_u64 v[6:7], s[0:1], 0, v[176:177]
	s_mov_b32 m0, s93
	s_nop 0
	global_load_lds_dwordx4 v[6:7], off
	v_lshl_add_u64 v[6:7], s[0:1], 0, v[172:173]
	s_mov_b32 m0, s78
	s_nop 0
	global_load_lds_dwordx4 v[6:7], off
	s_waitcnt vmcnt(8)
	s_waitcnt lgkmcnt(0)
	s_barrier
	s_setprio 1
	s_waitcnt lgkmcnt(0)
	v_mfma_f32_16x16x32_bf16 v[60:63], v[132:135], v[164:167], v[60:63]
	v_mfma_f32_16x16x32_bf16 v[52:55], v[140:143], v[164:167], v[52:55]
	v_mfma_f32_16x16x32_bf16 v[44:47], v[132:135], v[184:187], v[44:47]
	v_mfma_f32_16x16x32_bf16 v[36:39], v[140:143], v[184:187], v[36:39]
	v_mfma_f32_16x16x32_bf16 v[28:31], v[132:135], v[196:199], v[28:31]
	v_mfma_f32_16x16x32_bf16 v[20:23], v[140:143], v[196:199], v[20:23]
	v_mfma_f32_16x16x32_bf16 v[12:15], v[132:135], v[210:213], v[12:15]
	v_mfma_f32_16x16x32_bf16 v[2:5], v[140:143], v[210:213], v[2:5]
	v_mfma_f32_16x16x32_bf16 v[60:63], v[136:139], v[168:171], v[60:63]
	v_mfma_f32_16x16x32_bf16 v[52:55], v[144:147], v[168:171], v[52:55]
	v_mfma_f32_16x16x32_bf16 v[44:47], v[136:139], v[188:191], v[44:47]
	v_mfma_f32_16x16x32_bf16 v[36:39], v[144:147], v[188:191], v[36:39]
	v_mfma_f32_16x16x32_bf16 v[28:31], v[136:139], v[200:203], v[28:31]
	v_mfma_f32_16x16x32_bf16 v[20:23], v[144:147], v[200:203], v[20:23]
	v_mfma_f32_16x16x32_bf16 v[12:15], v[136:139], v[214:217], v[12:15]
	v_mfma_f32_16x16x32_bf16 v[4:7], v[144:147], v[214:217], v[2:5]
	v_mfma_f32_16x16x32_bf16 v[64:67], v[148:151], v[164:167], v[64:67]
	v_mfma_f32_16x16x32_bf16 v[56:59], v[156:159], v[164:167], v[56:59]
	v_mfma_f32_16x16x32_bf16 v[48:51], v[148:151], v[184:187], v[48:51]
	v_mfma_f32_16x16x32_bf16 v[40:43], v[156:159], v[184:187], v[40:43]
	v_mfma_f32_16x16x32_bf16 v[32:35], v[148:151], v[196:199], v[32:35]
	v_mfma_f32_16x16x32_bf16 v[24:27], v[156:159], v[196:199], v[24:27]
	v_mfma_f32_16x16x32_bf16 v[16:19], v[148:151], v[210:213], v[16:19]
	v_mfma_f32_16x16x32_bf16 v[8:11], v[156:159], v[210:213], v[8:11]
	v_mfma_f32_16x16x32_bf16 v[64:67], v[152:155], v[168:171], v[64:67]
	v_mfma_f32_16x16x32_bf16 v[56:59], v[160:163], v[168:171], v[56:59]
	v_mfma_f32_16x16x32_bf16 v[48:51], v[152:155], v[188:191], v[48:51]
	v_mfma_f32_16x16x32_bf16 v[40:43], v[160:163], v[188:191], v[40:43]
	v_mfma_f32_16x16x32_bf16 v[32:35], v[152:155], v[200:203], v[32:35]
	v_mfma_f32_16x16x32_bf16 v[24:27], v[160:163], v[200:203], v[24:27]
	v_mfma_f32_16x16x32_bf16 v[16:19], v[152:155], v[214:217], v[16:19]
	v_mfma_f32_16x16x32_bf16 v[8:11], v[160:163], v[214:217], v[8:11]
	s_setprio 0
	s_barrier
	s_add_u32 s6, s6, 0x100
	s_addc_u32 s7, s7, 0
	s_add_u32 s54, s54, 0x100
	s_addc_u32 s55, s55, 0
	s_add_i32 s56, s56, -2
	s_cmp_ge_u32 s57, s18
	s_mov_b32 s0, s57
	s_cbranch_scc0 .LBB0_1180
	s_and_b64 vcc, exec, s[76:77]
	s_cbranch_vccz .LBB0_1183
	s_barrier
